# GLU epilogue: the eight gate loads issued together at the top instead of one per row group
# speedup vs baseline: 1.0145x; 1.0046x over previous
.LBB0_616:
	v_lshl_add_u32 v146, s20, 8, v148
	v_lshl_or_b32 v144, s21, 7, v150
	v_ashrrev_i32_e32 v147, 31, v146
	v_ashrrev_i32_e32 v145, 31, v144
	v_lshlrev_b64 v[154:155], 13, v[146:147]
	v_lshl_add_u64 v[154:155], s[8:9], 0, v[154:155]
	v_lshlrev_b64 v[144:145], 1, v[144:145]
	v_lshl_add_u64 v[154:155], v[154:155], 0, v[144:145]
	v_add_co_u32_e32 v216, vcc, 0x20000, v154
	v_addc_co_u32_e32 v217, vcc, 0, v155, vcc
	global_load_dwordx4 v[220:223], v[216:217], off
	v_add_co_u32_e32 v216, vcc, 0x40000, v154
	v_addc_co_u32_e32 v217, vcc, 0, v155, vcc
	global_load_dwordx4 v[224:227], v[216:217], off
	v_add_co_u32_e32 v216, vcc, 0x60000, v154
	v_addc_co_u32_e32 v217, vcc, 0, v155, vcc
	global_load_dwordx4 v[228:231], v[216:217], off
	v_add_co_u32_e32 v216, vcc, 0x100000, v154
	v_addc_co_u32_e32 v217, vcc, 0, v155, vcc
	global_load_dwordx4 v[232:235], v[216:217], off
	v_add_co_u32_e32 v216, vcc, 0x120000, v154
	v_addc_co_u32_e32 v217, vcc, 0, v155, vcc
	global_load_dwordx4 v[236:239], v[216:217], off
	v_add_co_u32_e32 v216, vcc, 0x140000, v154
	v_addc_co_u32_e32 v217, vcc, 0, v155, vcc
	global_load_dwordx4 v[240:243], v[216:217], off
	v_add_co_u32_e32 v216, vcc, 0x160000, v154
	v_addc_co_u32_e32 v217, vcc, 0, v155, vcc
	global_load_dwordx4 v[244:247], v[216:217], off
	global_load_dwordx4 v[154:157], v[154:155], off
	v_mul_f32_e32 v116, 0xbfb8aa3b, v116
	v_mul_f32_e32 v117, 0xbfb8aa3b, v117
	v_exp_f32_e32 v116, v116
	v_exp_f32_e32 v117, v117
	v_mul_f32_e32 v112, 0xbfb8aa3b, v112
	v_mul_f32_e32 v113, 0xbfb8aa3b, v113
	v_mul_f32_e32 v114, 0xbfb8aa3b, v114
	v_mul_f32_e32 v115, 0xbfb8aa3b, v115
	v_mul_f32_e32 v118, 0xbfb8aa3b, v118
	v_mul_f32_e32 v119, 0xbfb8aa3b, v119
	v_exp_f32_e32 v112, v112
	v_exp_f32_e32 v113, v113
	v_exp_f32_e32 v114, v114
	v_exp_f32_e32 v115, v115
	v_exp_f32_e32 v118, v118
	v_exp_f32_e32 v119, v119
	v_add_f32_e32 v116, 1.0, v116
	v_add_f32_e32 v117, 1.0, v117
	v_rcp_f32_e32 v116, v116
	v_rcp_f32_e32 v117, v117
	v_add_f32_e32 v112, 1.0, v112
	v_add_f32_e32 v113, 1.0, v113
	v_add_f32_e32 v114, 1.0, v114
	v_add_f32_e32 v115, 1.0, v115
	v_add_f32_e32 v118, 1.0, v118
	v_add_f32_e32 v119, 1.0, v119
	v_rcp_f32_e32 v112, v112
	v_rcp_f32_e32 v113, v113
	v_rcp_f32_e32 v114, v114
	v_rcp_f32_e32 v115, v115
	v_rcp_f32_e32 v118, v118
	v_rcp_f32_e32 v119, v119
	v_mul_f32_e32 v100, 0xbfb8aa3b, v100
	v_mul_f32_e32 v101, 0xbfb8aa3b, v101
	v_exp_f32_e32 v100, v100
	v_exp_f32_e32 v101, v101
	v_mul_f32_e32 v96, 0xbfb8aa3b, v96
	v_mul_f32_e32 v97, 0xbfb8aa3b, v97
	v_mul_f32_e32 v98, 0xbfb8aa3b, v98
	v_mul_f32_e32 v99, 0xbfb8aa3b, v99
	v_mul_f32_e32 v102, 0xbfb8aa3b, v102
	v_mul_f32_e32 v103, 0xbfb8aa3b, v103
	v_exp_f32_e32 v96, v96
	v_exp_f32_e32 v97, v97
	v_exp_f32_e32 v98, v98
	v_exp_f32_e32 v99, v99
	v_exp_f32_e32 v102, v102
	v_exp_f32_e32 v103, v103
	v_add_f32_e32 v100, 1.0, v100
	v_add_f32_e32 v101, 1.0, v101
	v_rcp_f32_e32 v100, v100
	v_rcp_f32_e32 v101, v101
	v_add_f32_e32 v96, 1.0, v96
	v_add_f32_e32 v97, 1.0, v97
	v_add_f32_e32 v98, 1.0, v98
	v_add_f32_e32 v99, 1.0, v99
	v_add_f32_e32 v102, 1.0, v102
	v_add_f32_e32 v103, 1.0, v103
	v_rcp_f32_e32 v96, v96
	v_rcp_f32_e32 v97, v97
	v_rcp_f32_e32 v98, v98
	v_rcp_f32_e32 v99, v99
	v_rcp_f32_e32 v102, v102
	v_rcp_f32_e32 v103, v103
	v_mul_f32_e32 v84, 0xbfb8aa3b, v84
	v_mul_f32_e32 v85, 0xbfb8aa3b, v85
	v_exp_f32_e32 v84, v84
	v_exp_f32_e32 v85, v85
	v_mul_f32_e32 v80, 0xbfb8aa3b, v80
	v_mul_f32_e32 v81, 0xbfb8aa3b, v81
	v_mul_f32_e32 v82, 0xbfb8aa3b, v82
	v_mul_f32_e32 v83, 0xbfb8aa3b, v83
	v_mul_f32_e32 v86, 0xbfb8aa3b, v86
	v_mul_f32_e32 v87, 0xbfb8aa3b, v87
	v_exp_f32_e32 v80, v80
	v_exp_f32_e32 v81, v81
	v_exp_f32_e32 v82, v82
	v_exp_f32_e32 v83, v83
	v_exp_f32_e32 v86, v86
	s_waitcnt vmcnt(0)
	v_lshlrev_b32_e32 v158, 16, v154
	v_and_b32_e32 v159, 0xffff0000, v154
	v_lshlrev_b32_e32 v160, 16, v156
	v_and_b32_e32 v161, 0xffff0000, v156
	v_lshlrev_b32_e32 v156, 16, v157
	v_and_b32_e32 v157, 0xffff0000, v157
	v_pk_mul_f32 v[124:125], v[124:125], v[158:159]
	v_lshlrev_b32_e32 v154, 16, v155
	v_and_b32_e32 v155, 0xffff0000, v155
	v_pk_mul_f32 v[116:117], v[116:117], v[124:125]
	v_pk_mul_f32 v[120:121], v[120:121], v[160:161]
	v_pk_mul_f32 v[122:123], v[122:123], v[156:157]
	v_pk_mul_f32 v[126:127], v[126:127], v[154:155]
	v_pk_mul_f32 v[122:123], v[114:115], v[122:123]
	v_pk_mul_f32 v[114:115], v[112:113], v[120:121]
	v_cvt_pk_bf16_f32 v112, v116, v117
	v_lshlrev_b64 v[116:117], 12, v[146:147]
	v_pk_mul_f32 v[118:119], v[118:119], v[126:127]
	v_lshl_add_u64 v[116:117], s[96:97], 0, v[116:117]
	v_cvt_pk_bf16_f32 v113, v118, v119
	v_cvt_pk_bf16_f32 v114, v114, v115
	v_cvt_pk_bf16_f32 v115, v122, v123
	v_lshl_add_u64 v[116:117], v[116:117], 0, v[144:145]
	global_store_dwordx4 v[116:117], v[112:115], off
	v_exp_f32_e32 v87, v87
	v_add_f32_e32 v84, 1.0, v84
	v_or_b32_e32 v112, 16, v146
	v_ashrrev_i32_e32 v113, 31, v112
	v_lshlrev_b64 v[114:115], 13, v[112:113]
	v_lshl_add_u64 v[114:115], s[8:9], 0, v[114:115]
	v_lshl_add_u64 v[114:115], v[114:115], 0, v[144:145]
	v_mov_b32_e32 v114, v220
	v_mov_b32_e32 v115, v221
	v_mov_b32_e32 v116, v222
	v_mov_b32_e32 v117, v223
	v_add_f32_e32 v85, 1.0, v85
	v_rcp_f32_e32 v84, v84
	v_rcp_f32_e32 v85, v85
	v_add_f32_e32 v80, 1.0, v80
	v_add_f32_e32 v81, 1.0, v81
	v_add_f32_e32 v82, 1.0, v82
	v_add_f32_e32 v83, 1.0, v83
	v_add_f32_e32 v86, 1.0, v86
	v_add_f32_e32 v87, 1.0, v87
	v_rcp_f32_e32 v80, v80
	v_rcp_f32_e32 v81, v81
	v_rcp_f32_e32 v82, v82
	v_rcp_f32_e32 v83, v83
	v_rcp_f32_e32 v86, v86
	v_rcp_f32_e32 v87, v87
	v_mul_f32_e32 v68, 0xbfb8aa3b, v68
	v_mul_f32_e32 v69, 0xbfb8aa3b, v69
	v_exp_f32_e32 v68, v68
	v_exp_f32_e32 v69, v69
	v_mul_f32_e32 v64, 0xbfb8aa3b, v64
	v_mul_f32_e32 v65, 0xbfb8aa3b, v65
	v_mul_f32_e32 v66, 0xbfb8aa3b, v66
	v_mul_f32_e32 v67, 0xbfb8aa3b, v67
	v_mul_f32_e32 v70, 0xbfb8aa3b, v70
	v_mul_f32_e32 v71, 0xbfb8aa3b, v71
	v_exp_f32_e32 v64, v64
	v_exp_f32_e32 v65, v65
	v_exp_f32_e32 v66, v66
	v_exp_f32_e32 v67, v67
	v_exp_f32_e32 v70, v70
	v_exp_f32_e32 v71, v71
	v_add_f32_e32 v68, 1.0, v68
	v_add_f32_e32 v69, 1.0, v69
	v_rcp_f32_e32 v68, v68
	v_rcp_f32_e32 v69, v69
	v_add_f32_e32 v64, 1.0, v64
	v_add_f32_e32 v65, 1.0, v65
	v_add_f32_e32 v66, 1.0, v66
	v_add_f32_e32 v67, 1.0, v67
	v_add_f32_e32 v70, 1.0, v70
	v_add_f32_e32 v71, 1.0, v71
	v_rcp_f32_e32 v64, v64
	v_rcp_f32_e32 v65, v65
	v_rcp_f32_e32 v66, v66
	v_rcp_f32_e32 v67, v67
	v_rcp_f32_e32 v70, v70
	v_rcp_f32_e32 v71, v71
	v_mul_f32_e32 v52, 0xbfb8aa3b, v52
	v_mul_f32_e32 v53, 0xbfb8aa3b, v53
	v_exp_f32_e32 v52, v52
	v_exp_f32_e32 v53, v53
	v_mul_f32_e32 v48, 0xbfb8aa3b, v48
	v_mul_f32_e32 v49, 0xbfb8aa3b, v49
	v_mul_f32_e32 v50, 0xbfb8aa3b, v50
	v_mul_f32_e32 v51, 0xbfb8aa3b, v51
	v_mul_f32_e32 v54, 0xbfb8aa3b, v54
	v_mul_f32_e32 v55, 0xbfb8aa3b, v55
	v_exp_f32_e32 v48, v48
	v_exp_f32_e32 v49, v49
	v_exp_f32_e32 v50, v50
	v_exp_f32_e32 v51, v51
	v_exp_f32_e32 v54, v54
	v_exp_f32_e32 v55, v55
	v_add_f32_e32 v52, 1.0, v52
	v_add_f32_e32 v53, 1.0, v53
	v_rcp_f32_e32 v52, v52
	v_rcp_f32_e32 v53, v53
	v_add_f32_e32 v48, 1.0, v48
	v_add_f32_e32 v49, 1.0, v49
	v_add_f32_e32 v50, 1.0, v50
	v_add_f32_e32 v51, 1.0, v51
	v_add_f32_e32 v54, 1.0, v54
	v_add_f32_e32 v55, 1.0, v55
	v_rcp_f32_e32 v48, v48
	v_rcp_f32_e32 v49, v49
	v_rcp_f32_e32 v50, v50
	v_rcp_f32_e32 v51, v51
	v_rcp_f32_e32 v54, v54
	v_rcp_f32_e32 v55, v55
	s_waitcnt vmcnt(0)
	v_lshlrev_b32_e32 v118, 16, v114
	v_and_b32_e32 v119, 0xffff0000, v114
	v_lshlrev_b32_e32 v120, 16, v116
	v_and_b32_e32 v121, 0xffff0000, v116
	v_lshlrev_b32_e32 v116, 16, v117
	v_and_b32_e32 v117, 0xffff0000, v117
	v_pk_mul_f32 v[108:109], v[108:109], v[118:119]
	v_lshlrev_b32_e32 v114, 16, v115
	v_and_b32_e32 v115, 0xffff0000, v115
	v_pk_mul_f32 v[100:101], v[100:101], v[108:109]
	v_pk_mul_f32 v[104:105], v[104:105], v[120:121]
	v_pk_mul_f32 v[106:107], v[106:107], v[116:117]
	v_pk_mul_f32 v[110:111], v[110:111], v[114:115]
	v_pk_mul_f32 v[106:107], v[98:99], v[106:107]
	v_pk_mul_f32 v[98:99], v[96:97], v[104:105]
	v_cvt_pk_bf16_f32 v96, v100, v101
	v_lshlrev_b64 v[100:101], 12, v[112:113]
	v_pk_mul_f32 v[102:103], v[102:103], v[110:111]
	v_lshl_add_u64 v[100:101], s[96:97], 0, v[100:101]
	v_cvt_pk_bf16_f32 v97, v102, v103
	v_cvt_pk_bf16_f32 v98, v98, v99
	v_cvt_pk_bf16_f32 v99, v106, v107
	v_lshl_add_u64 v[100:101], v[100:101], 0, v[144:145]
	global_store_dwordx4 v[100:101], v[96:99], off
	v_mul_f32_e32 v36, 0xbfb8aa3b, v36
	v_mul_f32_e32 v37, 0xbfb8aa3b, v37
	v_or_b32_e32 v96, 32, v146
	v_ashrrev_i32_e32 v97, 31, v96
	v_lshlrev_b64 v[98:99], 13, v[96:97]
	v_lshl_add_u64 v[98:99], s[8:9], 0, v[98:99]
	v_lshl_add_u64 v[98:99], v[98:99], 0, v[144:145]
	v_mov_b32_e32 v98, v224
	v_mov_b32_e32 v99, v225
	v_mov_b32_e32 v100, v226
	v_mov_b32_e32 v101, v227
	v_exp_f32_e32 v36, v36
	v_exp_f32_e32 v37, v37
	v_mul_f32_e32 v32, 0xbfb8aa3b, v32
	v_mul_f32_e32 v33, 0xbfb8aa3b, v33
	v_mul_f32_e32 v34, 0xbfb8aa3b, v34
	v_mul_f32_e32 v35, 0xbfb8aa3b, v35
	v_mul_f32_e32 v38, 0xbfb8aa3b, v38
	v_mul_f32_e32 v39, 0xbfb8aa3b, v39
	v_exp_f32_e32 v32, v32
	v_exp_f32_e32 v33, v33
	v_exp_f32_e32 v34, v34
	v_exp_f32_e32 v35, v35
	v_exp_f32_e32 v38, v38
	v_exp_f32_e32 v39, v39
	v_add_f32_e32 v36, 1.0, v36
	v_add_f32_e32 v37, 1.0, v37
	v_rcp_f32_e32 v36, v36
	v_rcp_f32_e32 v37, v37
	v_add_f32_e32 v32, 1.0, v32
	v_add_f32_e32 v33, 1.0, v33
	v_add_f32_e32 v34, 1.0, v34
	v_add_f32_e32 v35, 1.0, v35
	v_add_f32_e32 v38, 1.0, v38
	v_add_f32_e32 v39, 1.0, v39
	v_rcp_f32_e32 v32, v32
	v_rcp_f32_e32 v33, v33
	v_rcp_f32_e32 v34, v34
	v_rcp_f32_e32 v35, v35
	v_rcp_f32_e32 v38, v38
	v_rcp_f32_e32 v39, v39
	v_mul_f32_e32 v20, 0xbfb8aa3b, v20
	v_mul_f32_e32 v21, 0xbfb8aa3b, v21
	v_exp_f32_e32 v20, v20
	v_exp_f32_e32 v21, v21
	v_mul_f32_e32 v16, 0xbfb8aa3b, v16
	v_mul_f32_e32 v17, 0xbfb8aa3b, v17
	v_mul_f32_e32 v18, 0xbfb8aa3b, v18
	v_mul_f32_e32 v19, 0xbfb8aa3b, v19
	v_mul_f32_e32 v22, 0xbfb8aa3b, v22
	v_mul_f32_e32 v23, 0xbfb8aa3b, v23
	v_exp_f32_e32 v16, v16
	v_exp_f32_e32 v17, v17
	v_exp_f32_e32 v18, v18
	v_exp_f32_e32 v19, v19
	v_exp_f32_e32 v22, v22
	v_exp_f32_e32 v23, v23
	v_add_f32_e32 v20, 1.0, v20
	v_add_f32_e32 v21, 1.0, v21
	v_rcp_f32_e32 v20, v20
	v_rcp_f32_e32 v21, v21
	v_add_f32_e32 v16, 1.0, v16
	v_add_f32_e32 v17, 1.0, v17
	v_add_f32_e32 v18, 1.0, v18
	v_add_f32_e32 v19, 1.0, v19
	v_add_f32_e32 v22, 1.0, v22
	v_add_f32_e32 v23, 1.0, v23
	v_rcp_f32_e32 v16, v16
	v_rcp_f32_e32 v17, v17
	v_rcp_f32_e32 v18, v18
	v_rcp_f32_e32 v19, v19
	v_rcp_f32_e32 v22, v22
	v_rcp_f32_e32 v23, v23
	v_mul_f32_e32 v4, 0xbfb8aa3b, v4
	v_mul_f32_e32 v5, 0xbfb8aa3b, v5
	v_exp_f32_e32 v4, v4
	v_exp_f32_e32 v5, v5
	v_mul_f32_e32 v0, 0xbfb8aa3b, v0
	v_mul_f32_e32 v1, 0xbfb8aa3b, v1
	v_mul_f32_e32 v2, 0xbfb8aa3b, v2
	v_mul_f32_e32 v3, 0xbfb8aa3b, v3
	v_mul_f32_e32 v6, 0xbfb8aa3b, v6
	v_mul_f32_e32 v7, 0xbfb8aa3b, v7
	v_exp_f32_e32 v0, v0
	v_exp_f32_e32 v1, v1
	v_exp_f32_e32 v2, v2
	v_exp_f32_e32 v3, v3
	v_exp_f32_e32 v6, v6
	v_exp_f32_e32 v7, v7
	v_add_f32_e32 v4, 1.0, v4
	s_waitcnt vmcnt(0)
	v_lshlrev_b32_e32 v102, 16, v98
	v_and_b32_e32 v103, 0xffff0000, v98
	v_lshlrev_b32_e32 v104, 16, v100
	v_and_b32_e32 v105, 0xffff0000, v100
	v_lshlrev_b32_e32 v100, 16, v101
	v_and_b32_e32 v101, 0xffff0000, v101
	v_pk_mul_f32 v[92:93], v[92:93], v[102:103]
	v_lshlrev_b32_e32 v98, 16, v99
	v_and_b32_e32 v99, 0xffff0000, v99
	v_pk_mul_f32 v[84:85], v[84:85], v[92:93]
	v_pk_mul_f32 v[88:89], v[88:89], v[104:105]
	v_pk_mul_f32 v[90:91], v[90:91], v[100:101]
	v_pk_mul_f32 v[94:95], v[94:95], v[98:99]
	v_pk_mul_f32 v[90:91], v[82:83], v[90:91]
	v_pk_mul_f32 v[82:83], v[80:81], v[88:89]
	v_cvt_pk_bf16_f32 v80, v84, v85
	v_lshlrev_b64 v[84:85], 12, v[96:97]
	v_pk_mul_f32 v[86:87], v[86:87], v[94:95]
	v_lshl_add_u64 v[84:85], s[96:97], 0, v[84:85]
	v_cvt_pk_bf16_f32 v81, v86, v87
	v_cvt_pk_bf16_f32 v82, v82, v83
	v_cvt_pk_bf16_f32 v83, v90, v91
	v_lshl_add_u64 v[84:85], v[84:85], 0, v[144:145]
	global_store_dwordx4 v[84:85], v[80:83], off
	v_add_f32_e32 v5, 1.0, v5
	v_rcp_f32_e32 v4, v4
	v_or_b32_e32 v80, 48, v146
	v_ashrrev_i32_e32 v81, 31, v80
	v_lshlrev_b64 v[82:83], 13, v[80:81]
	v_lshl_add_u64 v[82:83], s[8:9], 0, v[82:83]
	v_lshl_add_u64 v[82:83], v[82:83], 0, v[144:145]
	v_mov_b32_e32 v82, v228
	v_mov_b32_e32 v83, v229
	v_mov_b32_e32 v84, v230
	v_mov_b32_e32 v85, v231
	v_rcp_f32_e32 v5, v5
	v_add_f32_e32 v0, 1.0, v0
	v_add_f32_e32 v1, 1.0, v1
	v_add_f32_e32 v2, 1.0, v2
	v_add_f32_e32 v3, 1.0, v3
	v_add_f32_e32 v6, 1.0, v6
	v_add_f32_e32 v7, 1.0, v7
	v_rcp_f32_e32 v0, v0
	v_rcp_f32_e32 v1, v1
	v_rcp_f32_e32 v2, v2
	v_rcp_f32_e32 v3, v3
	v_rcp_f32_e32 v6, v6
	v_rcp_f32_e32 v7, v7
	s_mov_b64 s[20:21], -1
	s_andn2_b64 vcc, exec, s[38:39]
	s_waitcnt vmcnt(0)
	v_lshlrev_b32_e32 v86, 16, v82
	v_and_b32_e32 v87, 0xffff0000, v82
	v_lshlrev_b32_e32 v88, 16, v84
	v_and_b32_e32 v89, 0xffff0000, v84
	v_lshlrev_b32_e32 v84, 16, v85
	v_and_b32_e32 v85, 0xffff0000, v85
	v_pk_mul_f32 v[76:77], v[76:77], v[86:87]
	v_lshlrev_b32_e32 v82, 16, v83
	v_and_b32_e32 v83, 0xffff0000, v83
	v_pk_mul_f32 v[68:69], v[68:69], v[76:77]
	v_pk_mul_f32 v[72:73], v[72:73], v[88:89]
	v_pk_mul_f32 v[74:75], v[74:75], v[84:85]
	v_pk_mul_f32 v[78:79], v[78:79], v[82:83]
	v_pk_mul_f32 v[74:75], v[66:67], v[74:75]
	v_pk_mul_f32 v[66:67], v[64:65], v[72:73]
	v_cvt_pk_bf16_f32 v64, v68, v69
	v_lshlrev_b64 v[68:69], 12, v[80:81]
	v_pk_mul_f32 v[70:71], v[70:71], v[78:79]
	v_lshl_add_u64 v[68:69], s[96:97], 0, v[68:69]
	v_cvt_pk_bf16_f32 v65, v70, v71
	v_cvt_pk_bf16_f32 v66, v66, v67
	v_cvt_pk_bf16_f32 v67, v74, v75
	v_lshl_add_u64 v[68:69], v[68:69], 0, v[144:145]
	global_store_dwordx4 v[68:69], v[64:67], off
	s_nop 1
	v_add_u32_e32 v64, 0x80, v146
	v_ashrrev_i32_e32 v65, 31, v64
	v_lshlrev_b64 v[66:67], 13, v[64:65]
	v_lshl_add_u64 v[66:67], s[8:9], 0, v[66:67]
	v_lshl_add_u64 v[66:67], v[66:67], 0, v[144:145]
	v_mov_b32_e32 v66, v232
	v_mov_b32_e32 v67, v233
	v_mov_b32_e32 v68, v234
	v_mov_b32_e32 v69, v235
	s_waitcnt vmcnt(0)
	v_lshlrev_b32_e32 v70, 16, v66
	v_and_b32_e32 v71, 0xffff0000, v66
	v_lshlrev_b32_e32 v72, 16, v68
	v_and_b32_e32 v73, 0xffff0000, v68
	v_lshlrev_b32_e32 v68, 16, v69
	v_and_b32_e32 v69, 0xffff0000, v69
	v_pk_mul_f32 v[60:61], v[60:61], v[70:71]
	v_lshlrev_b32_e32 v66, 16, v67
	v_and_b32_e32 v67, 0xffff0000, v67
	v_pk_mul_f32 v[52:53], v[52:53], v[60:61]
	v_pk_mul_f32 v[56:57], v[56:57], v[72:73]
	v_pk_mul_f32 v[58:59], v[58:59], v[68:69]
	v_pk_mul_f32 v[62:63], v[62:63], v[66:67]
	v_pk_mul_f32 v[58:59], v[50:51], v[58:59]
	v_pk_mul_f32 v[50:51], v[48:49], v[56:57]
	v_cvt_pk_bf16_f32 v48, v52, v53
	v_lshlrev_b64 v[52:53], 12, v[64:65]
	v_pk_mul_f32 v[54:55], v[54:55], v[62:63]
	v_lshl_add_u64 v[52:53], s[96:97], 0, v[52:53]
	v_cvt_pk_bf16_f32 v49, v54, v55
	v_cvt_pk_bf16_f32 v50, v50, v51
	v_cvt_pk_bf16_f32 v51, v58, v59
	v_lshl_add_u64 v[52:53], v[52:53], 0, v[144:145]
	global_store_dwordx4 v[52:53], v[48:51], off
	s_nop 1
	v_add_u32_e32 v48, 0x90, v146
	v_ashrrev_i32_e32 v49, 31, v48
	v_lshlrev_b64 v[50:51], 13, v[48:49]
	v_lshl_add_u64 v[50:51], s[8:9], 0, v[50:51]
	v_lshl_add_u64 v[50:51], v[50:51], 0, v[144:145]
	v_mov_b32_e32 v50, v236
	v_mov_b32_e32 v51, v237
	v_mov_b32_e32 v52, v238
	v_mov_b32_e32 v53, v239
	s_waitcnt vmcnt(0)
	v_lshlrev_b32_e32 v54, 16, v50
	v_and_b32_e32 v55, 0xffff0000, v50
	v_lshlrev_b32_e32 v56, 16, v52
	v_and_b32_e32 v57, 0xffff0000, v52
	v_lshlrev_b32_e32 v52, 16, v53
	v_and_b32_e32 v53, 0xffff0000, v53
	v_pk_mul_f32 v[44:45], v[44:45], v[54:55]
	v_lshlrev_b32_e32 v50, 16, v51
	v_and_b32_e32 v51, 0xffff0000, v51
	v_pk_mul_f32 v[36:37], v[36:37], v[44:45]
	v_pk_mul_f32 v[40:41], v[40:41], v[56:57]
	v_pk_mul_f32 v[42:43], v[42:43], v[52:53]
	v_pk_mul_f32 v[46:47], v[46:47], v[50:51]
	v_pk_mul_f32 v[42:43], v[34:35], v[42:43]
	v_pk_mul_f32 v[34:35], v[32:33], v[40:41]
	v_cvt_pk_bf16_f32 v32, v36, v37
	v_lshlrev_b64 v[36:37], 12, v[48:49]
	v_pk_mul_f32 v[38:39], v[38:39], v[46:47]
	v_lshl_add_u64 v[36:37], s[96:97], 0, v[36:37]
	v_cvt_pk_bf16_f32 v33, v38, v39
	v_cvt_pk_bf16_f32 v34, v34, v35
	v_cvt_pk_bf16_f32 v35, v42, v43
	v_lshl_add_u64 v[36:37], v[36:37], 0, v[144:145]
	global_store_dwordx4 v[36:37], v[32:35], off
	s_nop 1
	v_add_u32_e32 v32, 0xa0, v146
	v_ashrrev_i32_e32 v33, 31, v32
	v_lshlrev_b64 v[34:35], 13, v[32:33]
	v_lshl_add_u64 v[34:35], s[8:9], 0, v[34:35]
	v_lshl_add_u64 v[34:35], v[34:35], 0, v[144:145]
	v_mov_b32_e32 v34, v240
	v_mov_b32_e32 v35, v241
	v_mov_b32_e32 v36, v242
	v_mov_b32_e32 v37, v243
	s_waitcnt vmcnt(0)
	v_lshlrev_b32_e32 v38, 16, v34
	v_and_b32_e32 v39, 0xffff0000, v34
	v_lshlrev_b32_e32 v40, 16, v36
	v_and_b32_e32 v41, 0xffff0000, v36
	v_lshlrev_b32_e32 v36, 16, v37
	v_and_b32_e32 v37, 0xffff0000, v37
	v_pk_mul_f32 v[28:29], v[28:29], v[38:39]
	v_lshlrev_b32_e32 v34, 16, v35
	v_and_b32_e32 v35, 0xffff0000, v35
	v_pk_mul_f32 v[20:21], v[20:21], v[28:29]
	v_pk_mul_f32 v[24:25], v[24:25], v[40:41]
	v_pk_mul_f32 v[26:27], v[26:27], v[36:37]
	v_pk_mul_f32 v[30:31], v[30:31], v[34:35]
	v_pk_mul_f32 v[26:27], v[18:19], v[26:27]
	v_pk_mul_f32 v[18:19], v[16:17], v[24:25]
	v_cvt_pk_bf16_f32 v16, v20, v21
	v_lshlrev_b64 v[20:21], 12, v[32:33]
	v_pk_mul_f32 v[22:23], v[22:23], v[30:31]
	v_lshl_add_u64 v[20:21], s[96:97], 0, v[20:21]
	v_cvt_pk_bf16_f32 v17, v22, v23
	v_cvt_pk_bf16_f32 v18, v18, v19
	v_cvt_pk_bf16_f32 v19, v26, v27
	v_lshl_add_u64 v[20:21], v[20:21], 0, v[144:145]
	global_store_dwordx4 v[20:21], v[16:19], off
	s_nop 1
	v_add_u32_e32 v16, 0xb0, v146
	v_ashrrev_i32_e32 v17, 31, v16
	v_lshlrev_b64 v[18:19], 13, v[16:17]
	v_lshl_add_u64 v[18:19], s[8:9], 0, v[18:19]
	v_lshl_add_u64 v[18:19], v[18:19], 0, v[144:145]
	v_mov_b32_e32 v18, v244
	v_mov_b32_e32 v19, v245
	v_mov_b32_e32 v20, v246
	v_mov_b32_e32 v21, v247
	s_waitcnt vmcnt(0)
	v_lshlrev_b32_e32 v22, 16, v18
	v_and_b32_e32 v23, 0xffff0000, v18
	v_lshlrev_b32_e32 v24, 16, v20
	v_and_b32_e32 v25, 0xffff0000, v20
	v_lshlrev_b32_e32 v20, 16, v21
	v_and_b32_e32 v21, 0xffff0000, v21
	v_pk_mul_f32 v[12:13], v[12:13], v[22:23]
	v_lshlrev_b32_e32 v18, 16, v19
	v_and_b32_e32 v19, 0xffff0000, v19
	v_pk_mul_f32 v[4:5], v[4:5], v[12:13]
	v_pk_mul_f32 v[8:9], v[8:9], v[24:25]
	v_pk_mul_f32 v[10:11], v[10:11], v[20:21]
	v_pk_mul_f32 v[14:15], v[14:15], v[18:19]
	v_pk_mul_f32 v[10:11], v[2:3], v[10:11]
	v_pk_mul_f32 v[2:3], v[0:1], v[8:9]
	v_cvt_pk_bf16_f32 v0, v4, v5
	v_lshlrev_b64 v[4:5], 12, v[16:17]
	v_pk_mul_f32 v[6:7], v[6:7], v[14:15]
	v_lshl_add_u64 v[4:5], s[96:97], 0, v[4:5]
	v_cvt_pk_bf16_f32 v1, v6, v7
	v_cvt_pk_bf16_f32 v2, v2, v3
	v_cvt_pk_bf16_f32 v3, v10, v11
	v_lshl_add_u64 v[4:5], v[4:5], 0, v[144:145]
	global_store_dwordx4 v[4:5], v[0:3], off
	s_cbranch_vccnz .LBB0_605
	s_andn2_b64 vcc, exec, s[0:1]
	s_cbranch_vccnz .LBB0_604
	s_barrier
	s_branch .LBB0_604
